# flattened barrier release: non-leader WGs poll the top generation word directly, per-XCD XGEN relay hop and its atomic removed (on keep_v5 stack)
# speedup vs baseline: 1.0284x; 1.0034x over previous
.LBB0_138:
	s_or_b64 exec, exec, s[14:15]
	v_cvt_f32_u32_e32 v5, v3
	s_waitcnt vmcnt(0)
	v_readfirstlane_b32 s9, v4
	v_sub_u32_e32 v4, 0, v3
	v_rcp_iflag_f32_e32 v5, v5
	v_add_u32_e32 v6, s9, v0
	v_mul_f32_e32 v5, 0x4f7ffffe, v5
	v_cvt_u32_f32_e32 v5, v5
	v_mul_lo_u32 v0, v4, v5
	v_mul_hi_u32 v0, v5, v0
	v_add_u32_e32 v0, v5, v0
	v_mul_hi_u32 v0, v6, v0
	v_mul_lo_u32 v4, v0, v3
	v_sub_u32_e32 v4, v6, v4
	v_add_u32_e32 v5, 1, v0
	v_cmp_ge_u32_e32 vcc, v4, v3
	s_nop 1
	v_cndmask_b32_e32 v0, v0, v5, vcc
	v_sub_u32_e32 v5, v4, v3
	v_cndmask_b32_e32 v4, v4, v5, vcc
	v_add_u32_e32 v5, 1, v0
	v_cmp_ge_u32_e32 vcc, v4, v3
	v_add_u32_e32 v4, 1, v6
	s_nop 0
	v_cndmask_b32_e32 v0, v0, v5, vcc
	v_mul_lo_u32 v5, v3, v0
	v_add_u32_e32 v3, v5, v3
	v_cmp_ne_u32_e32 vcc, v4, v3
	s_and_saveexec_b64 s[12:13], vcc
	s_xor_b64 s[12:13], exec, s[12:13]
	s_cbranch_execz .LBB0_152
	s_waitcnt lgkmcnt(0)
	s_add_u32 s18, s4, 0x303500
	s_addc_u32 s19, s5, 0
	global_load_dword v2, v1, s[18:19] sc1
	s_waitcnt vmcnt(0)
	v_cmp_eq_u32_e32 vcc, v2, v0
	s_and_saveexec_b64 s[14:15], vcc
	s_cbranch_execz .LBB0_151
	s_add_u32 s16, s4, 0x300200
	s_addc_u32 s17, s5, 0
	s_mov_b32 s9, 1
	s_mov_b64 s[22:23], 0
	s_branch .LBB0_142

.LBB0_169:
	s_or_b64 exec, exec, s[4:5]
	s_mov_b64 s[4:5], exec
	v_mbcnt_lo_u32_b32 v0, s4, 0
	v_mbcnt_hi_u32_b32 v0, s5, v0
	v_cmp_eq_u32_e32 vcc, 0, v0
	s_waitcnt vmcnt(0)
	buffer_inv sc1
	s_and_saveexec_b64 s[12:13], vcc
	s_cbranch_execz .LBB0_171
	s_bcnt1_i32_b64 s4, s[4:5]
	v_mov_b32_e32 v0, s4
.LBB0_171:
	s_or_b64 exec, exec, s[12:13]
	s_waitcnt vmcnt(0)

.LBB0_276:
	s_or_b64 exec, exec, s[4:5]
	s_mov_b64 s[4:5], exec
	v_mbcnt_lo_u32_b32 v0, s4, 0
	v_mbcnt_hi_u32_b32 v0, s5, v0
	v_cmp_eq_u32_e32 vcc, 0, v0
	s_waitcnt vmcnt(0)
	buffer_inv sc1
	s_and_saveexec_b64 s[12:13], vcc
	s_cbranch_execz .LBB0_278
	s_bcnt1_i32_b64 s4, s[4:5]
	v_mov_b32_e32 v0, s4
.LBB0_278:
	s_or_b64 exec, exec, s[12:13]
	s_waitcnt vmcnt(0)

.LBB0_362:
	s_or_b64 exec, exec, s[4:5]
	s_mov_b64 s[4:5], exec
	v_mbcnt_lo_u32_b32 v0, s4, 0
	v_mbcnt_hi_u32_b32 v0, s5, v0
	v_cmp_eq_u32_e32 vcc, 0, v0
	s_waitcnt vmcnt(0)
	buffer_inv sc1
	s_and_saveexec_b64 s[12:13], vcc
	s_cbranch_execz .LBB0_364
	s_bcnt1_i32_b64 s4, s[4:5]
	v_mov_b32_e32 v0, s4
.LBB0_364:
	s_or_b64 exec, exec, s[12:13]
	s_waitcnt vmcnt(0)

.LBB0_448:
	s_or_b64 exec, exec, s[4:5]
	s_mov_b64 s[4:5], exec
	v_mbcnt_lo_u32_b32 v0, s4, 0
	v_mbcnt_hi_u32_b32 v0, s5, v0
	v_cmp_eq_u32_e32 vcc, 0, v0
	s_waitcnt vmcnt(0)
	buffer_inv sc1
	s_and_saveexec_b64 s[12:13], vcc
	s_cbranch_execz .LBB0_450
	s_bcnt1_i32_b64 s4, s[4:5]
	v_mov_b32_e32 v0, s4
.LBB0_450:
	s_or_b64 exec, exec, s[12:13]
	s_waitcnt vmcnt(0)

.LBB0_509:
	s_or_b64 exec, exec, s[4:5]
	s_mov_b64 s[4:5], exec
	v_mbcnt_lo_u32_b32 v0, s4, 0
	v_mbcnt_hi_u32_b32 v0, s5, v0
	v_cmp_eq_u32_e32 vcc, 0, v0
	s_waitcnt vmcnt(0)
	buffer_inv sc1
	s_and_saveexec_b64 s[12:13], vcc
	s_cbranch_execz .LBB0_511
	s_bcnt1_i32_b64 s4, s[4:5]
	v_mov_b32_e32 v0, s4
.LBB0_511:
	s_or_b64 exec, exec, s[12:13]
	s_waitcnt vmcnt(0)

.LBB0_666:
	s_or_b64 exec, exec, s[4:5]
	s_mov_b64 s[4:5], exec
	v_mbcnt_lo_u32_b32 v0, s4, 0
	v_mbcnt_hi_u32_b32 v0, s5, v0
	v_cmp_eq_u32_e32 vcc, 0, v0
	s_waitcnt vmcnt(0)
	buffer_inv sc1
	s_and_saveexec_b64 s[12:13], vcc
	s_cbranch_execz .LBB0_668
	s_bcnt1_i32_b64 s4, s[4:5]
	v_mov_b32_e32 v0, s4
.LBB0_668:
	s_or_b64 exec, exec, s[12:13]
	s_waitcnt vmcnt(0)

.LBB0_765:
	s_or_b64 exec, exec, s[4:5]
	s_mov_b64 s[4:5], exec
	v_mbcnt_lo_u32_b32 v0, s4, 0
	v_mbcnt_hi_u32_b32 v0, s5, v0
	v_cmp_eq_u32_e32 vcc, 0, v0
	s_waitcnt vmcnt(0)
	buffer_inv sc1
	s_and_saveexec_b64 s[12:13], vcc
	s_cbranch_execz .LBB0_767
	s_bcnt1_i32_b64 s4, s[4:5]
	v_mov_b32_e32 v0, s4
.LBB0_767:
	s_or_b64 exec, exec, s[12:13]
	s_waitcnt vmcnt(0)

.LBB0_802:
	s_or_b64 exec, exec, s[14:15]
	v_cvt_f32_u32_e32 v5, v3
	s_waitcnt vmcnt(0)
	v_readfirstlane_b32 s9, v4
	v_sub_u32_e32 v4, 0, v3
	v_rcp_iflag_f32_e32 v5, v5
	v_add_u32_e32 v6, s9, v0
	v_mul_f32_e32 v5, 0x4f7ffffe, v5
	v_cvt_u32_f32_e32 v5, v5
	v_mul_lo_u32 v0, v4, v5
	v_mul_hi_u32 v0, v5, v0
	v_add_u32_e32 v0, v5, v0
	v_mul_hi_u32 v0, v6, v0
	v_mul_lo_u32 v4, v0, v3
	v_sub_u32_e32 v4, v6, v4
	v_add_u32_e32 v5, 1, v0
	v_cmp_ge_u32_e32 vcc, v4, v3
	s_nop 1
	v_cndmask_b32_e32 v0, v0, v5, vcc
	v_sub_u32_e32 v5, v4, v3
	v_cndmask_b32_e32 v4, v4, v5, vcc
	v_add_u32_e32 v5, 1, v0
	v_cmp_ge_u32_e32 vcc, v4, v3
	v_add_u32_e32 v4, 1, v6
	s_nop 0
	v_cndmask_b32_e32 v0, v0, v5, vcc
	v_mul_lo_u32 v5, v3, v0
	v_add_u32_e32 v3, v5, v3
	v_cmp_ne_u32_e32 vcc, v4, v3
	s_and_saveexec_b64 s[12:13], vcc
	s_xor_b64 s[12:13], exec, s[12:13]
	s_cbranch_execz .LBB0_816
	s_waitcnt lgkmcnt(0)
	s_add_u32 s24, s4, 0x303500
	s_addc_u32 s25, s5, 0
	global_load_dword v2, v1, s[24:25] sc1
	s_waitcnt vmcnt(0)
	v_cmp_eq_u32_e32 vcc, v2, v0
	s_and_saveexec_b64 s[14:15], vcc
	s_cbranch_execz .LBB0_815
	s_add_u32 s22, s4, 0x300200
	s_addc_u32 s23, s5, 0
	s_mov_b32 s9, 1
	s_mov_b64 s[26:27], 0
	s_branch .LBB0_806

.LBB0_833:
	s_or_b64 exec, exec, s[4:5]
	s_mov_b64 s[4:5], exec
	v_mbcnt_lo_u32_b32 v0, s4, 0
	v_mbcnt_hi_u32_b32 v0, s5, v0
	v_cmp_eq_u32_e32 vcc, 0, v0
	s_waitcnt vmcnt(0)
	buffer_inv sc1
	s_and_saveexec_b64 s[14:15], vcc
	s_cbranch_execz .LBB0_835
	s_bcnt1_i32_b64 s4, s[4:5]
	v_mov_b32_e32 v0, s4
.LBB0_835:
	s_or_b64 exec, exec, s[14:15]
	s_waitcnt vmcnt(0)

.LBB0_902:
	s_or_b64 exec, exec, s[4:5]
	s_mov_b64 s[4:5], exec
	v_mbcnt_lo_u32_b32 v0, s4, 0
	v_mbcnt_hi_u32_b32 v0, s5, v0
	v_cmp_eq_u32_e32 vcc, 0, v0
	s_waitcnt vmcnt(0)
	buffer_inv sc1
	s_and_saveexec_b64 s[14:15], vcc
	s_cbranch_execz .LBB0_904
	s_bcnt1_i32_b64 s4, s[4:5]
	v_mov_b32_e32 v0, s4
.LBB0_904:
	s_or_b64 exec, exec, s[14:15]
	s_waitcnt vmcnt(0)

.LBB0_1125:
	s_or_b64 exec, exec, s[4:5]
	s_mov_b64 s[4:5], exec
	v_mbcnt_lo_u32_b32 v0, s4, 0
	v_mbcnt_hi_u32_b32 v0, s5, v0
	v_cmp_eq_u32_e32 vcc, 0, v0
	s_waitcnt vmcnt(0)
	buffer_inv sc1
	s_and_saveexec_b64 s[12:13], vcc
	s_cbranch_execz .LBB0_105
	s_bcnt1_i32_b64 s4, s[4:5]
	v_mov_b32_e32 v0, s4
	s_branch .LBB0_105
